# v28 + fuse the two combine-max ops before the rescale check into one v_max3 (block-B max folded only in the rare path)
# baseline (speedup 1.0000x reference)
; #define MFMA32(a, b, c) __builtin_amdgcn_mfma_f32_32x32x16_bf16((a), (b), (c), 0, 0, 0)
; __device__ __forceinline__ void attn_unit2(const bf16_t* Qm, const bf16_t* KVm, const bf16_t* P1, bf16_t* OP, int q0, int h, int klat, int nlat, int kctx, int nt, uchar* lds, bool nostore = false) {
;     ...
;         { const uchar* kb = Kt + buf * KT_BYTES + l32 * KROW + hi * 16;
; #pragma unroll
;           for (int s = 0; s < 6; ++s) { const bf16x8 a0 = *(const bf16x8*)(kb + s * 32), a1 = *(const bf16x8*)(kb + 32 * KROW + s * 32);
;               sA0 = MFMA32(a0, qa[s], sA0); sA1 = MFMA32(a1, qa[s], sA1); sB0 = MFMA32(a0, qb[s], sB0); sB1 = MFMA32(a1, qb[s], sB1); } }
.LBB0_1117:
	s_and_b32 s4, s9, 1
	s_mul_i32 s5, s4, 0x3400
	v_add_u32_e32 v0, s5, v226
	ds_read_b128 v[66:69], v0
	ds_read_b128 v[70:73], v0 offset:32
	ds_read_b128 v[74:77], v0 offset:6656
	ds_read_b128 v[234:237], v0 offset:6688
	v_mfma_f32_32x32x16_bf16 v[114:129], v[208:211], v[216:219], 0
	v_mfma_f32_32x32x16_bf16 v[98:113], v[208:211], v[190:193], 0
	s_waitcnt lgkmcnt(3)
	v_mfma_f32_32x32x16_bf16 v[114:129], v[66:69], v[130:133], v[114:129]
	v_mfma_f32_32x32x16_bf16 v[98:113], v[66:69], v[170:173], v[98:113]
	s_waitcnt lgkmcnt(2)
	v_mfma_f32_32x32x16_bf16 v[114:129], v[70:73], v[134:137], v[114:129]
	v_mfma_f32_32x32x16_bf16 v[98:113], v[70:73], v[138:141], v[98:113]
	ds_read_b128 v[66:69], v0 offset:64
	ds_read_b128 v[70:73], v0 offset:96
	ds_read_b128 v[238:241], v0 offset:6720
	ds_read_b128 v[242:245], v0 offset:6752
	s_waitcnt lgkmcnt(3)
	v_mfma_f32_32x32x16_bf16 v[114:129], v[66:69], v[146:149], v[114:129]
	v_mfma_f32_32x32x16_bf16 v[98:113], v[66:69], v[142:145], v[98:113]
	v_mfma_f32_32x32x16_bf16 v[82:97], v[208:211], v[216:219], 0
	v_mfma_f32_32x32x16_bf16 v[82:97], v[74:77], v[130:133], v[82:97]
	s_waitcnt lgkmcnt(2)
	v_mfma_f32_32x32x16_bf16 v[114:129], v[70:73], v[150:153], v[114:129]
	v_mfma_f32_32x32x16_bf16 v[98:113], v[70:73], v[154:157], v[98:113]
	ds_read_b128 v[66:69], v0 offset:128
	ds_read_b128 v[70:73], v0 offset:160
	ds_read_b128 v[246:249], v0 offset:6784
	ds_read_b128 v[212:215], v0 offset:6816
	v_mfma_f32_32x32x16_bf16 v[82:97], v[234:237], v[134:137], v[82:97]
	s_waitcnt lgkmcnt(3)
	v_mfma_f32_32x32x16_bf16 v[114:129], v[66:69], v[162:165], v[114:129]
	v_mfma_f32_32x32x16_bf16 v[98:113], v[66:69], v[158:161], v[98:113]
	v_mfma_f32_32x32x16_bf16 v[82:97], v[238:241], v[146:149], v[82:97]
	s_waitcnt lgkmcnt(2)
	v_mfma_f32_32x32x16_bf16 v[114:129], v[70:73], v[166:169], v[114:129]
	v_mfma_f32_32x32x16_bf16 v[98:113], v[70:73], v[174:177], v[98:113]
	s_nop 10
	v_max_f32_e32 v0, v114, v115
	v_mfma_f32_32x32x16_bf16 v[66:81], v[74:77], v[170:173], 0
	v_mfma_f32_32x32x16_bf16 v[66:81], v[208:211], v[190:193], v[66:81]
	v_mfma_f32_32x32x16_bf16 v[82:97], v[242:245], v[150:153], v[82:97]
	v_mfma_f32_32x32x16_bf16 v[66:81], v[234:237], v[138:141], v[66:81]
	s_waitcnt lgkmcnt(1)
	v_mfma_f32_32x32x16_bf16 v[82:97], v[246:249], v[162:165], v[82:97]
	v_mfma_f32_32x32x16_bf16 v[66:81], v[238:241], v[142:145], v[66:81]
	s_waitcnt lgkmcnt(0)
	v_mfma_f32_32x32x16_bf16 v[82:97], v[212:215], v[166:169], v[82:97]
	v_mfma_f32_32x32x16_bf16 v[66:81], v[242:245], v[154:157], v[66:81]
	s_nop 10
	v_max3_f32 v234, v116, v117, v83
	v_max3_f32 v0, v0, v82, v84
	v_max3_f32 v0, v0, v85, v118
	v_max3_f32 v234, v234, v120, v121
	v_max3_f32 v0, v0, v119, v86
	v_max3_f32 v234, v234, v88, v89
	v_max3_f32 v0, v0, v87, v122
	v_mfma_f32_32x32x16_bf16 v[66:81], v[246:249], v[158:161], v[66:81]
	v_mfma_f32_32x32x16_bf16 v[66:81], v[212:215], v[174:177], v[66:81]
	v_max3_f32 v234, v234, v124, v125
	v_max3_f32 v0, v0, v123, v90
	v_max3_f32 v234, v234, v92, v93
	v_max3_f32 v0, v0, v91, v126
	v_max3_f32 v234, v234, v128, v129
	v_max3_f32 v0, v0, v127, v94
	v_max3_f32 v234, v234, v96, v97
	v_max3_f32 v0, v0, v95, v234
	v_max3_f32 v235, v98, v99, v100
	v_max3_f32 v236, v101, v102, v103
	v_max3_f32 v235, v235, v104, v105
	v_max3_f32 v236, v236, v106, v107
	v_max3_f32 v235, v235, v108, v109
	v_max3_f32 v236, v236, v110, v111
	v_max3_f32 v235, v235, v112, v113
	v_max3_f32 v236, v236, v66, v67
	v_max3_f32 v235, v235, v68, v69
	v_max3_f32 v236, v236, v70, v71
	v_max3_f32 v235, v235, v72, v73
	v_max3_f32 v236, v236, v74, v75
	v_max3_f32 v235, v235, v76, v77
	v_max3_f32 v236, v236, v78, v79
	v_max3_f32 v235, v235, v80, v81
	v_max3_f32 v237, v0, v235, v236
	v_cmp_lt_f32_e32 vcc, 0x41000000, v237
	s_cmp_eq_u32 s9, 0
	s_cbranch_scc1 .Latt_rare
	s_cbranch_vccz .LBB0_1121
.Latt_rare:
	v_max_f32_e32 v235, v235, v236
	ds_bpermute_b32 v234, v227, v0
	ds_bpermute_b32 v236, v227, v235
	s_waitcnt lgkmcnt(0)
	v_max_f32_e32 v0, v0, v234
	v_max_f32_e32 v235, v235, v236
